# first grid sync (after phase 0) uses the XCD-hierarchical barrier like all later steps
# speedup vs baseline: 1.0019x; 1.0019x over previous
; DI unsigned xb_ld(unsigned* p) { return __hip_atomic_load(p, __ATOMIC_RELAXED, __HIP_MEMORY_SCOPE_AGENT); }
; DI void xcd_barrier_complete(unsigned* bar, unsigned x, unsigned& nloc, unsigned& nx) {
;   const unsigned G = gridDim.x * gridDim.y * gridDim.z;
;   unsigned sum, cnt, mine, sp = 0u;
;   for (;;) {
;     sum = 0u; cnt = 0u; mine = 0u;
; #pragma unroll
;     for (unsigned j = 0; j < 16; ++j) { const unsigned c = xb_ld(&bar[XB_XCNT(j)]); sum += c; cnt += (c > 0u) ? 1u : 0u; mine = (j == x) ? c : mine; }
;     if (sum == G) break;
;     __builtin_amdgcn_s_sleep(1);
;     if ((++sp & 255u) == 0u) { if (xb_ld(&bar[XB_TMO])) break; if (sp > XB_SPIN_CAP) { atomicAdd(&bar[XB_TMO], 1u); break; } }
;   }
;   nloc = mine > 0u ? mine : 1u; nx = cnt > 0u ? cnt : 1u;
; }
; DI void xcd_barrier(const XcdBarrier& b) {
;   asm volatile("s_waitcnt vmcnt(0)" ::: "memory");
;   __syncthreads();
;   if (threadIdx.x == 0) {
;     unsigned* bar = b.bar;
;     __builtin_amdgcn_s_waitcnt(0);
;     unsigned nloc = b.st[0], nx = b.st[1];
;     if (nloc == 0u) { xcd_barrier_complete(bar, b.x, nloc, nx); b.st[0] = nloc; b.st[1] = nx; }
.LBB0_1166:
	v_readlane_b32 s0, v254, 63
	v_readlane_b32 s1, v255, 0
	s_and_b64 vcc, exec, s[0:1]
	v_readlane_b32 s4, v254, 33
	v_readlane_b32 s6, v254, 35
	v_readlane_b32 s7, v254, 36
	v_mov_b32 v0, s6
	v_mov_b32 v2, s7
	s_getreg_b32 s6, hwreg(HW_REG_XCC_ID, 0, 4)
	s_waitcnt vmcnt(0)
	v_readlane_b32 s5, v254, 34
	v_readfirstlane_b32 s4, v0
	v_readfirstlane_b32 s5, v2
	s_waitcnt vmcnt(0) lgkmcnt(0)
	s_barrier
	s_and_saveexec_b64 s[0:1], s[56:57]
	v_readlane_b32 s54, v255, 1
	s_cbranch_execz .LBB0_1220
	v_readlane_b32 s7, v253, 57
	s_waitcnt vmcnt(0) expcnt(0) lgkmcnt(0)
	s_and_b32 s6, s6, 15
	v_mov_b32_e32 v0, s7
	ds_read_b32 v3, v0
	v_readlane_b32 s7, v253, 58
	s_waitcnt lgkmcnt(0)
	v_cmp_ne_u32_e32 vcc, 0, v3
	v_mov_b32_e32 v0, s7
	ds_read_b32 v2, v0
	s_cbranch_vccnz .LBB0_1184
	s_add_u32 s8, s4, 0x7990e00
	s_addc_u32 s9, s5, 0
	s_add_u32 s10, s4, 0x7991000
	s_addc_u32 s11, s5, 0
	s_add_u32 s12, s4, 0x7991100
	s_addc_u32 s13, s5, 0
	s_add_u32 s14, s4, 0x7991200
	s_addc_u32 s15, s5, 0
	s_add_u32 s16, s4, 0x7991300
	s_addc_u32 s17, s5, 0
	s_add_u32 s18, s4, 0x7991400
	s_addc_u32 s19, s5, 0
	s_add_u32 s20, s4, 0x7991500
	s_addc_u32 s21, s5, 0
	s_add_u32 s22, s4, 0x7991600
	s_addc_u32 s23, s5, 0
	s_add_u32 s24, s4, 0x7991700
	s_addc_u32 s25, s5, 0
	s_add_u32 s26, s4, 0x7991800
	s_addc_u32 s27, s5, 0
	s_add_u32 s28, s4, 0x7991900
	s_addc_u32 s29, s5, 0
	s_add_u32 s30, s4, 0x7991a00
	s_addc_u32 s31, s5, 0
	s_add_u32 s36, s4, 0x7991b00
	s_addc_u32 s37, s5, 0
	s_add_u32 s38, s4, 0x7991c00
	s_addc_u32 s39, s5, 0
	s_add_u32 s40, s4, 0x7991d00
	s_addc_u32 s41, s5, 0
	s_add_u32 s42, s4, 0x7991e00
	s_addc_u32 s43, s5, 0
	s_add_u32 s44, s4, 0x7991f00
	s_addc_u32 s45, s5, 0
	s_mov_b32 s7, 1
	s_branch .LBB0_1171
